# P7: bf16->f32 conversion of the Y0 loads deferred past the MFMA chain (counted vmcnt(38) instead of an immediate drain)
# speedup vs baseline: 1.0452x; 1.0021x over previous
; #define LAS __attribute__((address_space(3)))
; __device__ __forceinline__ float bf2f(bf16_t b) { return __uint_as_float(((unsigned)b) << 16); }
; #define ZACC(a) do { a[0] = (f32x4){0.f, 0.f, 0.f, 0.f}; a[1] = (f32x4){0.f, 0.f, 0.f, 0.f}; } while (0)
; __device__ __forceinline__ void rwkv_phase_c(const Ctx& C) {
;     ...
;         for (int cc = 0; cc < GCH; ++cc) {
;             const int c = g * GCH + cc, tok0 = c * 64; const size_t io = (size_t)(c * 8 + h) * 4096;
;             const float* Qi = Qg + io; const bf16_t* Yi = Y0g + io;
;             const LAS float* Pb = MAT(2 + (cc & 1)); const LAS bf16_t* Rb = (const LAS bf16_t*)MAT(6 + (cc & 1));
;             f32x4 n0 = (f32x4){0.f, 0.f, 0.f, 0.f}, n1 = n0; u32x4 rn = (u32x4){0u, 0u, 0u, 0u};
;             if (cc + 1 < GCH) { const f32x4* P4 = (const f32x4*)(Pg + io + 8 * 4096); n0 = P4[e0]; n1 = P4[e1]; rn = ((const u32x4*)(Rcg + io + 8 * 4096))[tid]; }
;             float qv[2][4], yv[2][4];
; #pragma unroll
;             for (int i = 0; i < 2; ++i)
; #pragma unroll
;                 for (int j = 0; j < 4; ++j) { const int r = mt * 16 + 4 * q + j, c2 = nc0 + 16 * i; qv[i][j] = Qi[r * 64 + c2]; yv[i][j] = bf2f(Yi[r * 64 + c2]); }
;             float vv[8], bo[8], gt[8];
; #pragma unroll
;             for (int u = 0; u < 8; ++u) { const int tok = tok0 + tg8 * 8 + u; vv[u] = zshift(zr, tok, 1024 + h * 64 + ci, muv); bo[u] = bon[(size_t)tok * 8 + h]; gt[u] = bf2f(Gg[(size_t)tok * GWD_ + h * 64 + ci]); }
;             f32x4 xy[2], xs[2]; ZACC(xy); ZACC(xs);
; #pragma unroll
;             for (int ks = 0; ks < 2; ++ks) {
;                 const bf16x8 a = *(const LAS bf16x8*)(Rb + mrow * BS + ks * 32 + q * 8);
;                 const bf16x8 h0 = *(const LAS bf16x8*)(SH + nc0 * BS + ks * 32 + q * 8), h1 = *(const LAS bf16x8*)(SH + (nc0 + 16) * BS + ks * 32 + q * 8);
;                 const bf16x8 l0 = *(const LAS bf16x8*)(SL + nc0 * BS + ks * 32 + q * 8), l1 = *(const LAS bf16x8*)(SL + (nc0 + 16) * BS + ks * 32 + q * 8);
;                 xy[0] = __builtin_amdgcn_mfma_f32_16x16x32_bf16(a, h0, xy[0], 0, 0, 0); xy[1] = __builtin_amdgcn_mfma_f32_16x16x32_bf16(a, h1, xy[1], 0, 0, 0);
;                 xy[0] = __builtin_amdgcn_mfma_f32_16x16x32_bf16(a, l0, xy[0], 0, 0, 0); xy[1] = __builtin_amdgcn_mfma_f32_16x16x32_bf16(a, l1, xy[1], 0, 0, 0);
;             }
;             mm_lds<false>(xs, MAT(0), Pb, mrow, nc0, q);
.LBB0_1066:
	s_add_i32 s11, s51, -1
	s_lshl_b64 s[14:15], s[16:17], 2
	s_add_u32 s14, s0, s14
	s_addc_u32 s15, s1, s15
	s_lshl_b64 s[16:17], s[16:17], 1
	s_add_u32 s16, s2, s16
	s_addc_u32 s17, s3, s17
	ds_read_b128 v[30:33], v77
	s_bitcmp1_b32 s11, 0
	s_cselect_b32 s42, 0x4400, 0
	v_add_u32_e32 v168, s42, v74
	v_add_u32_e32 v81, 0x8800, v168
	ds_read2_b32 v[42:43], v81 offset1:16
	ds_read_b128 v[34:37], v77 offset:64
	s_waitcnt lgkmcnt(1)
	v_mfma_f32_16x16x4_f32 v[38:41], v30, v42, 0
	v_lshl_add_u64 v[88:89], v[24:25], 1, s[16:17]
	v_lshl_add_u64 v[90:91], v[26:27], 1, s[16:17]
	v_lshl_add_u64 v[94:95], v[28:29], 1, s[16:17]
	ds_read2_b32 v[86:87], v81 offset0:204 offset1:220
	v_lshl_add_u64 v[92:93], v[28:29], 2, s[14:15]
	s_or_b32 s11, s11, 6
	s_mulk_i32 s11, 0x4400
	v_mfma_f32_16x16x4_f32 v[82:85], v30, v43, 0
	ds_read2_b32 v[42:43], v81 offset0:68 offset1:84
	s_andn2_b64 vcc, exec, s[6:7]
	s_waitcnt lgkmcnt(0)
	v_mfma_f32_16x16x4_f32 v[38:41], v31, v42, v[38:41]
	v_mfma_f32_16x16x4_f32 v[82:85], v31, v43, v[82:85]
	ds_read2_b32 v[30:31], v81 offset0:136 offset1:152
	v_lshl_add_u64 v[42:43], v[24:25], 2, s[14:15]
	s_waitcnt lgkmcnt(0)
	v_mfma_f32_16x16x4_f32 v[38:41], v32, v30, v[38:41]
	v_mfma_f32_16x16x4_f32 v[82:85], v32, v31, v[82:85]
	v_lshl_add_u64 v[30:31], v[14:15], 1, s[16:17]
	global_load_ushort v185, v[90:91], off
	global_load_ushort v186, v[94:95], off
	global_load_ushort v187, v[30:31], off
	global_load_ushort v188, v[88:89], off
	s_nop 0
	global_load_ushort v189, v[88:89], off offset:32
	s_nop 0
	global_load_dword v169, v[42:43], off offset:64
	global_load_ushort v190, v[30:31], off offset:32
	s_nop 0
	global_load_ushort v191, v[94:95], off offset:32
	s_nop 0
	global_load_dword v170, v[92:93], off offset:64
	s_nop 0
	global_load_ushort v192, v[90:91], off offset:32
	v_add_u32_e32 v91, 0x9800, v168
	v_mfma_f32_16x16x4_f32 v[38:41], v33, v86, v[38:41]
	v_mfma_f32_16x16x4_f32 v[30:33], v33, v87, v[82:85]
	ds_read2_b32 v[82:83], v91 offset0:64 offset1:80
	v_lshl_add_u64 v[84:85], v[14:15], 2, s[14:15]
	v_lshl_add_u64 v[86:87], v[26:27], 2, s[14:15]
	global_load_dword v171, v[42:43], off
	global_load_dword v172, v[84:85], off
	global_load_dword v173, v[84:85], off offset:64
	global_load_dword v174, v[92:93], off
	global_load_dword v175, v[86:87], off
	global_load_dword v176, v[86:87], off offset:64
	v_add_u32_e32 v42, s54, v76
	v_ashrrev_i32_e32 v43, 31, v42
	v_lshlrev_b64 v[92:93], 10, v[42:43]
	s_waitcnt lgkmcnt(0)
	v_mfma_f32_16x16x4_f32 v[38:41], v34, v82, v[38:41]
	v_mad_i64_i32 v[86:87], s[14:15], v42, s47, v[18:19]
	v_mfma_f32_16x16x4_f32 v[30:33], v34, v83, v[30:33]
	ds_read2_b32 v[82:83], v91 offset0:132 offset1:148
	v_max_i32_e32 v34, 1, v42
	v_add_u32_e32 v81, -1, v34
	v_mad_u64_u32 v[88:89], s[14:15], v81, s47, v[18:19]
	v_add_u32_e32 v81, 0xa800, v168
	s_waitcnt lgkmcnt(0)
	v_mfma_f32_16x16x4_f32 v[38:41], v35, v82, v[38:41]
	v_mfma_f32_16x16x4_f32 v[30:33], v35, v83, v[30:33]
	ds_read2_b32 v[34:35], v91 offset0:200 offset1:216
	v_lshlrev_b64 v[82:83], 5, v[42:43]
	v_lshl_add_u64 v[90:91], s[12:13], 0, v[82:83]
	s_waitcnt lgkmcnt(0)
	v_mfma_f32_16x16x4_f32 v[82:85], v36, v34, v[38:41]
	s_nop 3
	v_add_u32_e32 v40, 1, v42
	v_ashrrev_i32_e32 v41, 31, v40
	v_lshl_add_u64 v[38:39], v[20:21], 0, v[92:93]
	v_lshlrev_b64 v[92:93], 5, v[40:41]
	v_max_i32_e32 v34, 1, v40
	v_lshl_add_u64 v[98:99], s[12:13], 0, v[92:93]
	v_lshlrev_b64 v[92:93], 10, v[40:41]
	v_mfma_f32_16x16x4_f32 v[30:33], v36, v35, v[30:33]
	v_add_u32_e32 v36, 0x9c00, v168
	ds_read2_b32 v[94:95], v36 offset0:12 offset1:28
	v_add_u32_e32 v34, -1, v34
	v_lshl_add_u64 v[100:101], v[20:21], 0, v[92:93]
	v_mad_i64_i32 v[96:97], s[14:15], v40, s47, v[18:19]
	v_mad_u64_u32 v[34:35], s[14:15], v34, s47, v[18:19]
	s_waitcnt lgkmcnt(0)
	v_mfma_f32_16x16x4_f32 v[82:85], v37, v94, v[82:85]
	global_load_ushort v94, v[86:87], off offset:2048
	global_load_ushort v93, v[88:89], off offset:2048
	s_nop 0
	global_load_dword v88, v[90:91], off
	s_nop 0
	global_load_ushort v91, v[38:39], off
	global_load_ushort v92, v[96:97], off offset:2048
	global_load_ushort v90, v[34:35], off offset:2048
	global_load_dword v87, v[98:99], off
	global_load_ushort v89, v[100:101], off
	ds_read_b128 v[98:101], v77 offset:128
	ds_read_b128 v[112:115], v77 offset:192
	ds_read2_b32 v[34:35], v81 offset0:128 offset1:144
	v_add_u32_e32 v38, 2, v42
	ds_read2_b32 v[102:103], v81 offset0:196 offset1:212
	v_ashrrev_i32_e32 v39, 31, v38
	v_mfma_f32_16x16x4_f32 v[30:33], v37, v95, v[30:33]
	v_lshlrev_b64 v[36:37], 5, v[38:39]
	v_lshl_add_u64 v[110:111], s[12:13], 0, v[36:37]
	v_lshlrev_b64 v[36:37], 10, v[38:39]
	v_mad_i64_i32 v[96:97], s[14:15], v38, s47, v[18:19]
	s_waitcnt lgkmcnt(1)
	v_mfma_f32_16x16x4_f32 v[82:85], v98, v34, v[82:85]
	v_max_i32_e32 v34, 1, v38
	v_add_u32_e32 v34, -1, v34
	v_mad_u64_u32 v[104:105], s[14:15], v34, s47, v[18:19]
	v_mfma_f32_16x16x4_f32 v[30:33], v98, v35, v[30:33]
	v_lshl_add_u64 v[34:35], v[20:21], 0, v[36:37]
	v_add_u32_e32 v36, 3, v42
	v_ashrrev_i32_e32 v37, 31, v36
	v_max_i32_e32 v81, 1, v36
	v_add_u32_e32 v81, -1, v81
	v_lshlrev_b64 v[118:119], 10, v[36:37]
	v_mad_i64_i32 v[116:117], s[14:15], v36, s47, v[18:19]
	s_waitcnt lgkmcnt(0)
; #define LAS __attribute__((address_space(3)))
; __device__ __forceinline__ float bf2f(bf16_t b) { return __uint_as_float(((unsigned)b) << 16); }
; #define ZACC(a) do { a[0] = (f32x4){0.f, 0.f, 0.f, 0.f}; a[1] = (f32x4){0.f, 0.f, 0.f, 0.f}; } while (0)
; __device__ __forceinline__ void rwkv_phase_c(const Ctx& C) {
;     ...
;                 for (int j = 0; j < 4; ++j) { const int r = mt * 16 + 4 * q + j, c2 = nc0 + 16 * i; qv[i][j] = Qi[r * 64 + c2]; yv[i][j] = bf2f(Yi[r * 64 + c2]); }
;             float vv[8], bo[8], gt[8];
; #pragma unroll
;             for (int u = 0; u < 8; ++u) { const int tok = tok0 + tg8 * 8 + u; vv[u] = zshift(zr, tok, 1024 + h * 64 + ci, muv); bo[u] = bon[(size_t)tok * 8 + h]; gt[u] = bf2f(Gg[(size_t)tok * GWD_ + h * 64 + ci]); }
;             f32x4 xy[2], xs[2]; ZACC(xy); ZACC(xs);
; #pragma unroll
;             for (int ks = 0; ks < 2; ++ks) {
;                 const bf16x8 a = *(const LAS bf16x8*)(Rb + mrow * BS + ks * 32 + q * 8);
;                 const bf16x8 h0 = *(const LAS bf16x8*)(SH + nc0 * BS + ks * 32 + q * 8), h1 = *(const LAS bf16x8*)(SH + (nc0 + 16) * BS + ks * 32 + q * 8);
;                 const bf16x8 l0 = *(const LAS bf16x8*)(SL + nc0 * BS + ks * 32 + q * 8), l1 = *(const LAS bf16x8*)(SL + (nc0 + 16) * BS + ks * 32 + q * 8);
;                 xy[0] = __builtin_amdgcn_mfma_f32_16x16x32_bf16(a, h0, xy[0], 0, 0, 0); xy[1] = __builtin_amdgcn_mfma_f32_16x16x32_bf16(a, h1, xy[1], 0, 0, 0);
;                 xy[0] = __builtin_amdgcn_mfma_f32_16x16x32_bf16(a, l0, xy[0], 0, 0, 0); xy[1] = __builtin_amdgcn_mfma_f32_16x16x32_bf16(a, l1, xy[1], 0, 0, 0);
;             }
;             mm_lds<false>(xs, MAT(0), Pb, mrow, nc0, q);
; #pragma unroll
;             for (int i = 0; i < 2; ++i)
; #pragma unroll
;                 for (int j = 0; j < 4; ++j) { const int r = mt * 16 + 4 * q + j, c2 = nc0 + 16 * i; MAT(1)[r * MS + c2] = xy[i][j] + yv[i][j]; }
	v_mfma_f32_16x16x4_f32 v[106:109], v99, v102, v[82:85]
	v_lshlrev_b64 v[84:85], 5, v[36:37]
	v_mad_u64_u32 v[82:83], s[14:15], v81, s47, v[18:19]
	v_lshl_add_u64 v[84:85], s[12:13], 0, v[84:85]
	v_add_u32_e32 v81, 0xac00, v168
	v_lshl_add_u64 v[118:119], v[20:21], 0, v[118:119]
	v_mfma_f32_16x16x4_f32 v[30:33], v99, v103, v[30:33]
	global_load_ushort v103, v[96:97], off offset:2048
	s_nop 0
	global_load_ushort v104, v[104:105], off offset:2048
	s_nop 0
	global_load_dword v86, v[110:111], off
	global_load_ushort v97, v[34:35], off
	global_load_ushort v98, v[116:117], off offset:2048
	global_load_ushort v99, v[82:83], off offset:2048
	s_nop 0
	global_load_dword v85, v[84:85], off
	s_nop 0
	global_load_ushort v96, v[118:119], off
	ds_read2_b32 v[82:83], v81 offset0:8 offset1:24
	v_add_u32_e32 v34, 4, v42
	v_ashrrev_i32_e32 v35, 31, v34
	v_lshlrev_b64 v[116:117], 5, v[34:35]
	v_lshl_add_u64 v[126:127], s[12:13], 0, v[116:117]
	v_lshlrev_b64 v[120:121], 10, v[34:35]
	s_waitcnt lgkmcnt(0)
	v_mfma_f32_16x16x4_f32 v[106:109], v100, v82, v[106:109]
	v_max_i32_e32 v82, 1, v34
	v_add_u32_e32 v82, -1, v82
	v_mad_u64_u32 v[124:125], s[14:15], v82, s47, v[18:19]
	v_mad_i64_i32 v[110:111], s[14:15], v34, s47, v[18:19]
	v_mfma_f32_16x16x4_f32 v[116:119], v100, v83, v[30:33]
	ds_read2_b32 v[82:83], v81 offset0:76 offset1:92
	v_add_u32_e32 v32, 5, v42
	v_ashrrev_i32_e32 v33, 31, v32
	v_max_i32_e32 v81, 1, v32
	v_lshl_add_u64 v[30:31], v[20:21], 0, v[120:121]
	v_add_u32_e32 v81, -1, v81
	v_mad_u64_u32 v[130:131], s[14:15], v81, s47, v[18:19]
	s_waitcnt lgkmcnt(0)
	v_mfma_f32_16x16x4_f32 v[120:123], v101, v82, v[106:109]
	v_lshlrev_b64 v[106:107], 5, v[32:33]
	v_lshl_add_u64 v[132:133], s[12:13], 0, v[106:107]
	v_lshlrev_b64 v[106:107], 10, v[32:33]
	v_add_u32_e32 v81, s11, v73
	v_mad_i64_i32 v[128:129], s[14:15], v32, s47, v[18:19]
	v_lshl_add_u64 v[134:135], v[20:21], 0, v[106:107]
	global_load_ushort v109, v[110:111], off offset:2048
	s_nop 0
	global_load_ushort v110, v[124:125], off offset:2048
	global_load_dword v84, v[126:127], off
	global_load_ushort v106, v[30:31], off
	global_load_ushort v107, v[128:129], off offset:2048
	global_load_ushort v108, v[130:131], off offset:2048
	global_load_dword v82, v[132:133], off
	global_load_ushort v105, v[134:135], off
	ds_read_b128 v[124:127], v81
	ds_read_b128 v[128:131], v53
	v_add_u32_e32 v30, 0xb800, v168
	v_mfma_f32_16x16x4_f32 v[116:119], v101, v83, v[116:119]
	ds_read2_b32 v[100:101], v30 offset0:192 offset1:208
	ds_read_b128 v[132:135], v54
	ds_read_b128 v[136:139], v81 offset:64
	ds_read_b128 v[140:143], v53 offset:64
	ds_read_b128 v[144:147], v55
	ds_read_b128 v[148:151], v54 offset:64
	ds_read_b128 v[152:155], v56
	ds_read_b128 v[156:159], v55 offset:64
	v_add_u32_e32 v30, 6, v42
	v_ashrrev_i32_e32 v31, 31, v30
	v_max_i32_e32 v83, 1, v30
	s_waitcnt lgkmcnt(8)
	v_mfma_f32_16x16x32_bf16 v[128:131], v[124:127], v[128:131], 0
	v_mad_i64_i32 v[160:161], s[14:15], v30, s47, v[18:19]
	v_add_u32_e32 v83, -1, v83
	s_waitcnt lgkmcnt(6)
	v_mfma_f32_16x16x32_bf16 v[132:135], v[124:127], v[132:135], 0
	v_lshlrev_b64 v[164:165], 5, v[30:31]
	v_lshlrev_b64 v[166:167], 10, v[30:31]
	v_mad_u64_u32 v[162:163], s[14:15], v83, s47, v[18:19]
	s_waitcnt lgkmcnt(3)
	v_mfma_f32_16x16x32_bf16 v[128:131], v[124:127], v[144:147], v[128:131]
	v_lshl_add_u64 v[164:165], s[12:13], 0, v[164:165]
	ds_read_b128 v[144:147], v56 offset:64
	s_waitcnt lgkmcnt(2)
	v_mfma_f32_16x16x32_bf16 v[124:127], v[124:127], v[152:155], v[132:135]
	s_nop 2
	v_add_u32_e32 v134, 7, v42
	v_ashrrev_i32_e32 v135, 31, v134
	v_max_i32_e32 v81, 1, v134
	v_mfma_f32_16x16x32_bf16 v[128:131], v[136:139], v[140:143], v[128:131]
	v_mad_i64_i32 v[140:141], s[14:15], v134, s47, v[18:19]
	v_add_u32_e32 v81, -1, v81
	v_mfma_f32_16x16x32_bf16 v[124:127], v[136:139], v[148:151], v[124:127]
	v_lshlrev_b64 v[148:149], 5, v[134:135]
	v_lshlrev_b64 v[134:135], 10, v[134:135]
	v_lshl_add_u64 v[132:133], v[20:21], 0, v[166:167]
	v_mfma_f32_16x16x4_f32 v[120:123], v112, v100, v[120:123]
	v_mad_u64_u32 v[142:143], s[14:15], v81, s47, v[18:19]
	v_lshl_add_u64 v[148:149], s[12:13], 0, v[148:149]
	v_lshl_add_u64 v[134:135], v[20:21], 0, v[134:135]
	v_mfma_f32_16x16x4_f32 v[116:119], v112, v101, v[116:119]
	global_load_ushort v111, v[160:161], off offset:2048
	global_load_ushort v112, v[162:163], off offset:2048
	global_load_dword v83, v[164:165], off
	global_load_ushort v100, v[132:133], off
	global_load_ushort v101, v[140:141], off offset:2048
	global_load_ushort v102, v[142:143], off offset:2048
	global_load_dword v81, v[148:149], off
	global_load_ushort v95, v[134:135], off
	s_waitcnt lgkmcnt(1)
	v_mfma_f32_16x16x32_bf16 v[128:131], v[136:139], v[156:159], v[128:131]
	s_waitcnt lgkmcnt(0)
	v_mfma_f32_16x16x32_bf16 v[124:127], v[136:139], v[144:147], v[124:127]
	v_add_u32_e32 v136, 0xbc00, v168
	ds_read2_b32 v[132:133], v136 offset0:4 offset1:20
	ds_read2_b32 v[134:135], v136 offset0:72 offset1:88
	ds_read2_b32 v[136:137], v136 offset0:140 offset1:156
	s_nop 1
	s_waitcnt vmcnt(38)
	v_lshlrev_b32_e32 v179, 16, v185
	v_lshlrev_b32_e32 v177, 16, v187
	v_lshlrev_b32_e32 v178, 16, v188
	v_lshlrev_b32_e32 v182, 16, v189
	v_lshlrev_b32_e32 v184, 16, v191
	v_lshlrev_b32_e32 v181, 16, v190
	v_lshlrev_b32_e32 v183, 16, v192
	v_lshlrev_b32_e32 v180, 16, v186
	v_add_f32_e32 v128, v128, v177
	s_waitcnt lgkmcnt(2)
	v_mfma_f32_16x16x4_f32 v[120:123], v113, v132, v[120:123]
	v_add_f32_e32 v124, v124, v181
	v_add_u32_e32 v132, 0x4400, v78
	v_add_f32_e32 v129, v129, v178
	ds_write2_b32 v132, v128, v124 offset1:16
	v_add_f32_e32 v124, v125, v182
	v_add_f32_e32 v130, v130, v179
	ds_write2_b32 v132, v129, v124 offset0:68 offset1:84
	s_waitcnt lgkmcnt(3)
	v_mfma_f32_16x16x4_f32 v[120:123], v114, v134, v[120:123]
	v_add_f32_e32 v124, v126, v183
	v_add_f32_e32 v131, v131, v180
	ds_write2_b32 v132, v130, v124 offset0:136 offset1:152
	v_add_f32_e32 v124, v127, v184
	ds_write2_b32 v132, v131, v124 offset0:204 offset1:220
	s_waitcnt lgkmcnt(0)
	s_barrier
; #define LAS __attribute__((address_space(3)))
; __device__ __forceinline__ float bf2f(bf16_t b) { return __uint_as_float(((unsigned)b) << 16); }
; __device__ __forceinline__ bf16_t f2bf(float f) { return (bf16_t)(pk2(f, 0.f) & 0xffffu); }
; __device__ __forceinline__ void rwkv_phase_c(const Ctx& C) {
;     ...
;             __syncthreads();
; #pragma unroll
;             for (int i = 0; i < 2; ++i)
; #pragma unroll
;                 for (int j = 0; j < 4; ++j) { const int r = mt * 16 + 4 * q + j, c2 = nc0 + 16 * i; const float sv = xs[i][j] + qv[i][j];
;                     MAT(0)[r * MS + c2] = sv; const bf16_t hb = f2bf(sv); SH[r * BS + c2] = hb; SL[r * BS + c2] = f2bf(sv - bf2f(hb)); }
;             if (cc + 1 < GCH) {
;                 LAS float* Pn = MAT(2 + ((cc + 1) & 1));
;                 *(LAS f32x4*)(Pn + r0 * MS + c0) = n0; *(LAS f32x4*)(Pn + r1 * MS + c1) = n1;
;                 *(LAS u32x4*)((LAS bf16_t*)MAT(6 + ((cc + 1) & 1)) + rr8 * BS + cc8) = rn;
;             }
	v_mfma_f32_16x16x4_f32 v[120:123], v115, v136, v[120:123]
	v_mfma_f32_16x16x4_f32 v[116:119], v113, v133, v[116:119]
	s_waitcnt vmcnt(36)
	s_nop 7
	v_add_f32_e32 v120, v172, v120
	v_cvt_pk_bf16_f32 v124, v120, s0
	ds_write_b16 v57, v124
	v_lshlrev_b32_e32 v124, 16, v124
	v_sub_f32_e32 v124, v120, v124
	v_add_f32_e32 v113, v171, v121
	v_cvt_pk_bf16_f32 v124, v124, s0
	v_cvt_pk_bf16_f32 v121, v113, s0
	ds_write_b16 v58, v124
	ds_write_b16 v59, v121
	v_lshlrev_b32_e32 v121, 16, v121
	v_mfma_f32_16x16x4_f32 v[116:119], v114, v135, v[116:119]
	v_sub_f32_e32 v121, v113, v121
	v_cvt_pk_bf16_f32 v121, v121, s0
	ds_write_b16 v60, v121
	s_waitcnt vmcnt(33)
	v_add_f32_e32 v121, v175, v122
	v_cvt_pk_bf16_f32 v114, v121, s0
	ds_write_b16 v61, v114
	v_lshlrev_b32_e32 v114, 16, v114
	v_sub_f32_e32 v114, v121, v114
	v_cvt_pk_bf16_f32 v114, v114, s0
	ds_write_b16 v62, v114
	v_mfma_f32_16x16x4_f32 v[114:117], v115, v137, v[116:119]
	v_add_f32_e32 v118, v174, v123
	v_cvt_pk_bf16_f32 v119, v118, s0
	ds_write_b16 v63, v119
	v_lshlrev_b32_e32 v119, 16, v119
	v_sub_f32_e32 v119, v118, v119
	v_cvt_pk_bf16_f32 v119, v119, s0
	ds_write_b16 v64, v119
	s_nop 2
	v_add_f32_e32 v114, v173, v114
	v_cvt_pk_bf16_f32 v119, v114, s0
	ds_write_b16 v65, v119
	v_lshlrev_b32_e32 v119, 16, v119
	ds_write2_b32 v78, v120, v114 offset1:16
	v_sub_f32_e32 v114, v114, v119
	v_cvt_pk_bf16_f32 v114, v114, s0
	ds_write_b16 v66, v114
	v_add_f32_e32 v114, v169, v115
	ds_write2_b32 v78, v113, v114 offset0:68 offset1:84
	v_cvt_pk_bf16_f32 v113, v114, s0
	ds_write_b16 v67, v113
	v_lshlrev_b32_e32 v113, 16, v113
	v_sub_f32_e32 v113, v114, v113
	v_cvt_pk_bf16_f32 v113, v113, s0
	ds_write_b16 v68, v113
	s_waitcnt vmcnt(32)
	v_add_f32_e32 v113, v176, v116
	v_cvt_pk_bf16_f32 v114, v113, s0
	ds_write_b16 v69, v114
	v_lshlrev_b32_e32 v114, 16, v114
	ds_write2_b32 v78, v121, v113 offset0:136 offset1:152
	v_sub_f32_e32 v113, v113, v114
	v_cvt_pk_bf16_f32 v113, v113, s0
	ds_write_b16 v70, v113
	v_add_f32_e32 v113, v170, v117
	v_cvt_pk_bf16_f32 v114, v113, s0
	ds_write_b16 v71, v114
	v_lshlrev_b32_e32 v114, 16, v114
	ds_write2_b32 v78, v118, v113 offset0:204 offset1:220
	v_sub_f32_e32 v113, v113, v114
	v_cvt_pk_bf16_f32 v113, v113, s0
	ds_write_b16 v72, v113
	s_cbranch_vccnz .LBB0_1062
	s_bitcmp1_b32 s51, 0
	s_cselect_b32 s6, 0x4400, 0
	s_add_i32 s6, s6, 0
	v_add3_u32 v113, s6, v45, v46
	ds_write_b128 v113, v[10:13] offset:34816
	v_add3_u32 v10, s6, v47, v46
	s_add_i32 s6, s6, 0x19800
	ds_write_b128 v10, v[2:5] offset:34816
	v_add3_u32 v2, s6, v48, v49
	ds_write_b128 v2, v[6:9]
	s_branch .LBB0_1062
